# P3 epilogue hand-written, g1 gate vector fetched in the tile header
# speedup vs baseline: 1.0931x; 1.0007x over previous
.LBB0_1104:
	s_nop 7
	s_nop 7
	s_mul_hi_u32 s0, s37, 0xaaaaaaab
	s_lshr_b32 s12, s0, 2
	s_mul_i32 s0, s12, 6
	s_sub_i32 s0, s37, s0
	v_readlane_b32 s10, v246, 6
	s_add_i32 s10, s0, s10
	s_lshl_b32 s13, s10, 8
	v_readlane_b32 s48, v247, 57
	v_readlane_b32 s49, v247, 58
	s_lshl_b32 s0, s13, 11
	s_add_u32 s10, s48, s0
	s_addc_u32 s11, s49, 0
	s_lshl_b32 s0, s12, 8
	s_add_u32 s10, s10, s0
	s_addc_u32 s11, s11, 0
	v_lshl_add_u32 v202, v199, 2, v207
	v_lshlrev_b32_e32 v202, 11, v202
	v_lshl_add_u32 v202, v198, 1, v202
	v_add_u32_e32 v203, 0x1000, v202
	v_mul_f32_e32 v114, v178, v114
	v_mul_f32_e32 v98, v179, v98
	v_mul_f32_e32 v82, v180, v82
	v_mul_f32_e32 v66, v181, v66
	v_cvt_pk_bf16_f32 v190, v114, v98
	v_cvt_pk_bf16_f32 v191, v82, v66
	global_store_dwordx2 v202, v[190:191], s[10:11]
	v_mul_f32_e32 v115, v178, v115
	v_mul_f32_e32 v99, v179, v99
	v_mul_f32_e32 v83, v180, v83
	v_mul_f32_e32 v67, v181, v67
	v_cvt_pk_bf16_f32 v192, v115, v99
	v_cvt_pk_bf16_f32 v193, v83, v67
	global_store_dwordx2 v202, v[192:193], s[10:11] offset:2048
	v_mul_f32_e32 v116, v178, v116
	v_mul_f32_e32 v100, v179, v100
	v_mul_f32_e32 v84, v180, v84
	v_mul_f32_e32 v68, v181, v68
	v_cvt_pk_bf16_f32 v194, v116, v100
	v_cvt_pk_bf16_f32 v195, v84, v68
	global_store_dwordx2 v203, v[194:195], s[10:11]
	v_mul_f32_e32 v117, v178, v117
	v_mul_f32_e32 v101, v179, v101
	v_mul_f32_e32 v85, v180, v85
	v_mul_f32_e32 v69, v181, v69
	v_cvt_pk_bf16_f32 v216, v117, v101
	v_cvt_pk_bf16_f32 v217, v85, v69
	global_store_dwordx2 v203, v[216:217], s[10:11] offset:2048
	s_add_u32 s10, s10, 0x4000
	s_addc_u32 s11, s11, 0
	v_mul_f32_e32 v118, v178, v118
	v_mul_f32_e32 v102, v179, v102
	v_mul_f32_e32 v86, v180, v86
	v_mul_f32_e32 v70, v181, v70
	v_cvt_pk_bf16_f32 v190, v118, v102
	v_cvt_pk_bf16_f32 v191, v86, v70
	global_store_dwordx2 v202, v[190:191], s[10:11]
	v_mul_f32_e32 v119, v178, v119
	v_mul_f32_e32 v103, v179, v103
	v_mul_f32_e32 v87, v180, v87
	v_mul_f32_e32 v71, v181, v71
	v_cvt_pk_bf16_f32 v192, v119, v103
	v_cvt_pk_bf16_f32 v193, v87, v71
	global_store_dwordx2 v202, v[192:193], s[10:11] offset:2048
	v_mul_f32_e32 v120, v178, v120
	v_mul_f32_e32 v104, v179, v104
	v_mul_f32_e32 v88, v180, v88
	v_mul_f32_e32 v72, v181, v72
	v_cvt_pk_bf16_f32 v194, v120, v104
	v_cvt_pk_bf16_f32 v195, v88, v72
	global_store_dwordx2 v203, v[194:195], s[10:11]
	v_mul_f32_e32 v121, v178, v121
	v_mul_f32_e32 v105, v179, v105
	v_mul_f32_e32 v89, v180, v89
	v_mul_f32_e32 v73, v181, v73
	v_cvt_pk_bf16_f32 v216, v121, v105
	v_cvt_pk_bf16_f32 v217, v89, v73
	global_store_dwordx2 v203, v[216:217], s[10:11] offset:2048
	s_add_u32 s10, s10, 0x4000
	s_addc_u32 s11, s11, 0
	v_mul_f32_e32 v122, v178, v122
	v_mul_f32_e32 v106, v179, v106
	v_mul_f32_e32 v90, v180, v90
	v_mul_f32_e32 v74, v181, v74
	v_cvt_pk_bf16_f32 v190, v122, v106
	v_cvt_pk_bf16_f32 v191, v90, v74
	global_store_dwordx2 v202, v[190:191], s[10:11]
	v_mul_f32_e32 v123, v178, v123
	v_mul_f32_e32 v107, v179, v107
	v_mul_f32_e32 v91, v180, v91
	v_mul_f32_e32 v75, v181, v75
	v_cvt_pk_bf16_f32 v192, v123, v107
	v_cvt_pk_bf16_f32 v193, v91, v75
	global_store_dwordx2 v202, v[192:193], s[10:11] offset:2048
	v_mul_f32_e32 v124, v178, v124
	v_mul_f32_e32 v108, v179, v108
	v_mul_f32_e32 v92, v180, v92
	v_mul_f32_e32 v76, v181, v76
	v_cvt_pk_bf16_f32 v194, v124, v108
	v_cvt_pk_bf16_f32 v195, v92, v76
	global_store_dwordx2 v203, v[194:195], s[10:11]
	v_mul_f32_e32 v125, v178, v125
	v_mul_f32_e32 v109, v179, v109
	v_mul_f32_e32 v93, v180, v93
	v_mul_f32_e32 v77, v181, v77
	v_cvt_pk_bf16_f32 v216, v125, v109
	v_cvt_pk_bf16_f32 v217, v93, v77
	global_store_dwordx2 v203, v[216:217], s[10:11] offset:2048
	s_add_u32 s10, s10, 0x4000
	s_addc_u32 s11, s11, 0
	v_mul_f32_e32 v126, v178, v126
	v_mul_f32_e32 v110, v179, v110
	v_mul_f32_e32 v94, v180, v94
	v_mul_f32_e32 v78, v181, v78
	v_cvt_pk_bf16_f32 v190, v126, v110
	v_cvt_pk_bf16_f32 v191, v94, v78
	global_store_dwordx2 v202, v[190:191], s[10:11]
	v_mul_f32_e32 v127, v178, v127
	v_mul_f32_e32 v111, v179, v111
	v_mul_f32_e32 v95, v180, v95
	v_mul_f32_e32 v79, v181, v79
	v_cvt_pk_bf16_f32 v192, v127, v111
	v_cvt_pk_bf16_f32 v193, v95, v79
	global_store_dwordx2 v202, v[192:193], s[10:11] offset:2048
	v_mul_f32_e32 v128, v178, v128
	v_mul_f32_e32 v112, v179, v112
	v_mul_f32_e32 v96, v180, v96
	v_mul_f32_e32 v80, v181, v80
	v_cvt_pk_bf16_f32 v194, v128, v112
	v_cvt_pk_bf16_f32 v195, v96, v80
	global_store_dwordx2 v203, v[194:195], s[10:11]
	v_mul_f32_e32 v129, v178, v129
	v_mul_f32_e32 v113, v179, v113
	v_mul_f32_e32 v97, v180, v97
	v_mul_f32_e32 v81, v181, v81
	v_cvt_pk_bf16_f32 v216, v129, v113
	v_cvt_pk_bf16_f32 v217, v97, v81
	global_store_dwordx2 v203, v[216:217], s[10:11] offset:2048
	s_add_u32 s10, s10, 0x4000
	s_addc_u32 s11, s11, 0
	v_mul_f32_e32 v50, v178, v50
	v_mul_f32_e32 v34, v179, v34
	v_mul_f32_e32 v18, v180, v18
	v_mul_f32_e32 v2, v181, v2
	v_cvt_pk_bf16_f32 v190, v50, v34
	v_cvt_pk_bf16_f32 v191, v18, v2
	global_store_dwordx2 v202, v[190:191], s[10:11]
	v_mul_f32_e32 v51, v178, v51
	v_mul_f32_e32 v35, v179, v35
	v_mul_f32_e32 v19, v180, v19
	v_mul_f32_e32 v3, v181, v3
	v_cvt_pk_bf16_f32 v192, v51, v35
	v_cvt_pk_bf16_f32 v193, v19, v3
	global_store_dwordx2 v202, v[192:193], s[10:11] offset:2048
	v_mul_f32_e32 v52, v178, v52
	v_mul_f32_e32 v36, v179, v36
	v_mul_f32_e32 v20, v180, v20
	v_mul_f32_e32 v4, v181, v4
	v_cvt_pk_bf16_f32 v194, v52, v36
	v_cvt_pk_bf16_f32 v195, v20, v4
	global_store_dwordx2 v203, v[194:195], s[10:11]
	v_mul_f32_e32 v53, v178, v53
	v_mul_f32_e32 v37, v179, v37
	v_mul_f32_e32 v21, v180, v21
	v_mul_f32_e32 v5, v181, v5
	v_cvt_pk_bf16_f32 v216, v53, v37
	v_cvt_pk_bf16_f32 v217, v21, v5
	global_store_dwordx2 v203, v[216:217], s[10:11] offset:2048
	s_add_u32 s10, s10, 0x4000
	s_addc_u32 s11, s11, 0
	v_mul_f32_e32 v54, v178, v54
	v_mul_f32_e32 v38, v179, v38
	v_mul_f32_e32 v22, v180, v22
	v_mul_f32_e32 v6, v181, v6
	v_cvt_pk_bf16_f32 v190, v54, v38
	v_cvt_pk_bf16_f32 v191, v22, v6
	global_store_dwordx2 v202, v[190:191], s[10:11]
	v_mul_f32_e32 v55, v178, v55
	v_mul_f32_e32 v39, v179, v39
	v_mul_f32_e32 v23, v180, v23
	v_mul_f32_e32 v7, v181, v7
	v_cvt_pk_bf16_f32 v192, v55, v39
	v_cvt_pk_bf16_f32 v193, v23, v7
	global_store_dwordx2 v202, v[192:193], s[10:11] offset:2048
	v_mul_f32_e32 v56, v178, v56
	v_mul_f32_e32 v40, v179, v40
	v_mul_f32_e32 v24, v180, v24
	v_mul_f32_e32 v8, v181, v8
	v_cvt_pk_bf16_f32 v194, v56, v40
	v_cvt_pk_bf16_f32 v195, v24, v8
	global_store_dwordx2 v203, v[194:195], s[10:11]
	v_mul_f32_e32 v57, v178, v57
	v_mul_f32_e32 v41, v179, v41
	v_mul_f32_e32 v25, v180, v25
	v_mul_f32_e32 v9, v181, v9
	v_cvt_pk_bf16_f32 v216, v57, v41
	v_cvt_pk_bf16_f32 v217, v25, v9
	global_store_dwordx2 v203, v[216:217], s[10:11] offset:2048
	s_add_u32 s10, s10, 0x4000
	s_addc_u32 s11, s11, 0
	v_mul_f32_e32 v58, v178, v58
	v_mul_f32_e32 v42, v179, v42
	v_mul_f32_e32 v26, v180, v26
	v_mul_f32_e32 v10, v181, v10
	v_cvt_pk_bf16_f32 v190, v58, v42
	v_cvt_pk_bf16_f32 v191, v26, v10
	global_store_dwordx2 v202, v[190:191], s[10:11]
	v_mul_f32_e32 v59, v178, v59
	v_mul_f32_e32 v43, v179, v43
	v_mul_f32_e32 v27, v180, v27
	v_mul_f32_e32 v11, v181, v11
	v_cvt_pk_bf16_f32 v192, v59, v43
	v_cvt_pk_bf16_f32 v193, v27, v11
	global_store_dwordx2 v202, v[192:193], s[10:11] offset:2048
	v_mul_f32_e32 v60, v178, v60
	v_mul_f32_e32 v44, v179, v44
	v_mul_f32_e32 v28, v180, v28
	v_mul_f32_e32 v12, v181, v12
	v_cvt_pk_bf16_f32 v194, v60, v44
	v_cvt_pk_bf16_f32 v195, v28, v12
	global_store_dwordx2 v203, v[194:195], s[10:11]
	v_mul_f32_e32 v61, v178, v61
	v_mul_f32_e32 v45, v179, v45
	v_mul_f32_e32 v29, v180, v29
	v_mul_f32_e32 v13, v181, v13
	v_cvt_pk_bf16_f32 v216, v61, v45
	v_cvt_pk_bf16_f32 v217, v29, v13
	global_store_dwordx2 v203, v[216:217], s[10:11] offset:2048
	s_add_u32 s10, s10, 0x4000
	s_addc_u32 s11, s11, 0
	v_mul_f32_e32 v62, v178, v62
	v_mul_f32_e32 v46, v179, v46
	v_mul_f32_e32 v30, v180, v30
	v_mul_f32_e32 v14, v181, v14
	v_cvt_pk_bf16_f32 v190, v62, v46
	v_cvt_pk_bf16_f32 v191, v30, v14
	global_store_dwordx2 v202, v[190:191], s[10:11]
	v_mul_f32_e32 v63, v178, v63
	v_mul_f32_e32 v47, v179, v47
	v_mul_f32_e32 v31, v180, v31
	v_mul_f32_e32 v15, v181, v15
	v_cvt_pk_bf16_f32 v192, v63, v47
	v_cvt_pk_bf16_f32 v193, v31, v15
	global_store_dwordx2 v202, v[192:193], s[10:11] offset:2048
	v_mul_f32_e32 v64, v178, v64
	v_mul_f32_e32 v48, v179, v48
	v_mul_f32_e32 v32, v180, v32
	v_mul_f32_e32 v16, v181, v16
	v_cvt_pk_bf16_f32 v194, v64, v48
	v_cvt_pk_bf16_f32 v195, v32, v16
	global_store_dwordx2 v203, v[194:195], s[10:11]
	v_mul_f32_e32 v65, v178, v65
	v_mul_f32_e32 v49, v179, v49
	v_mul_f32_e32 v33, v180, v33
	v_mul_f32_e32 v17, v181, v17
	v_cvt_pk_bf16_f32 v216, v65, v49
	v_cvt_pk_bf16_f32 v217, v33, v17
	global_store_dwordx2 v203, v[216:217], s[10:11] offset:2048
	s_and_b64 vcc, exec, s[8:9]
	s_mov_b32 s37, s36
	s_cbranch_vccnz .LBB0_1112
.LBB0_1105:
	s_mul_hi_u32 s0, s37, 0xaaaaaaab
	s_lshr_b32 s12, s0, 2
	s_mul_i32 s0, s12, 6
	s_sub_i32 s0, s37, s0
	v_readlane_b32 s10, v246, 6
	s_add_i32 s10, s0, s10
	s_lshl_b32 s13, s10, 8
	s_add_i32 s11, s13, 0xfffff000
	s_lshr_b32 s11, s11, 11
	s_add_i32 s11, s11, 1
	s_cmp_gt_u32 s10, 15
	s_cselect_b32 s10, s11, 0
	s_add_i32 s10, s10, s68
	s_mul_hi_u32 s11, s10, 0x6000
	s_mulk_i32 s10, 0x6000
	v_readlane_b32 s38, v247, 51
	v_readlane_b32 s39, v247, 52
	s_add_u32 s10, s38, s10
	s_addc_u32 s11, s39, s11
	s_lshl_b32 s0, s12, 9
	s_add_u32 s10, s10, s0
	s_addc_u32 s11, s11, 0
	s_add_u32 s10, s10, 0x2000
	s_addc_u32 s11, s11, 0
	v_lshlrev_b32_e32 v2, 2, v198
	global_load_dwordx4 v[178:181], v2, s[10:11]
	s_add_i32 s36, s37, s86
	s_cmp_ge_i32 s36, s14
	s_cselect_b64 s[8:9], -1, 0
	s_and_b64 vcc, exec, s[8:9]
	s_mov_b64 s[10:11], s[6:7]
	s_mov_b64 s[12:13], s[4:5]
	s_mov_b32 s38, s35
	s_cbranch_vccnz .LBB0_1107
	s_mul_hi_u32 s38, s36, 0xaaaaaaab
	s_lshr_b32 s0, s38, 2
	s_mul_i32 s10, s0, 6
	s_sub_i32 s39, s36, s10
	v_readlane_b32 s10, v246, 6
	s_add_i32 s10, s39, s10
	s_lshl_b32 s10, s10, 19
	s_add_u32 s10, s20, s10
	s_addc_u32 s11, s21, 0
	s_lshl_b32 s0, s0, 7
	s_lshl_b64 s[12:13], s[0:1], 2
	s_add_u32 s12, s15, s12
	s_addc_u32 s13, s34, s13
	s_bfe_u32 s0, s38, 0x10002
	s_add_i32 s38, s0, s39
